# stack2: stack1 + relaxed first-iteration vmcnt waits in all four GEMM K-loops
# baseline (speedup 1.0000x reference)
.LBB0_194:
	v_add_u32_e32 v0, 0x10000, v214
	ds_read_b128 v[146:149], v0
	ds_read_b128 v[150:153], v0 offset:1024
	ds_read_b128 v[154:157], v0 offset:2048
	ds_read_b128 v[158:161], v0 offset:3072
	v_add_u32_e32 v0, 0x14000, v214
	ds_read_b128 v[130:133], v0
	ds_read_b128 v[134:137], v0 offset:1024
	ds_read_b128 v[138:141], v0 offset:2048
	ds_read_b128 v[142:145], v0 offset:3072
	ds_read_b128 v[186:189], v215
	ds_read_b128 v[190:193], v215 offset:1024
	ds_read_b128 v[178:181], v215 offset:2048
	ds_read_b128 v[182:185], v215 offset:3072
	ds_read_b128 v[170:173], v215 offset:4096
	ds_read_b128 v[174:177], v215 offset:5120
	ds_read_b128 v[162:165], v215 offset:6144
	ds_read_b128 v[166:169], v215 offset:7168
	s_add_u32 s38, s2, 0x40080
	s_addc_u32 s39, s3, 0
	s_mov_b32 m0, s73
	s_nop 0
	global_load_lds_dwordx4 v210, s[38:39]
	s_and_b64 vcc, exec, s[34:35]
	s_mov_b32 m0, s75
	s_nop 0
	global_load_lds_dwordx4 v212, s[38:39]
	s_mov_b64 s[38:39], -1
	s_cbranch_vccz .LBB0_196
	s_cmp_lg_i32 s93, -2
	s_cbranch_scc1 .Lwin0_n
	s_cmp_lt_u32 s74, 2
	s_cbranch_scc1 .Lwin0_n
	s_waitcnt vmcnt(22)
	s_branch .Lwin0_d

.Lwin0_d:
	s_mov_b64 s[38:39], 0

.LBB0_198:
	s_add_u32 s2, s2, 0x100
	s_addc_u32 s3, s3, 0
	s_waitcnt lgkmcnt(0)
	s_and_b64 s[36:37], s[36:37], exec
	s_cselect_b32 s39, s27, s3
	s_cselect_b32 s38, s78, s2
	s_cselect_b32 s37, s25, s92
	s_cselect_b32 s36, s79, s91
	s_barrier
	s_setprio 1
	s_waitcnt lgkmcnt(0)
	v_mfma_f32_16x16x32_bf16 v[126:129], v[146:149], v[186:189], v[126:129]
	v_mfma_f32_16x16x32_bf16 v[122:125], v[154:157], v[186:189], v[122:125]
	v_mfma_f32_16x16x32_bf16 v[110:113], v[146:149], v[178:181], v[110:113]
	v_mfma_f32_16x16x32_bf16 v[106:109], v[154:157], v[178:181], v[106:109]
	v_mfma_f32_16x16x32_bf16 v[94:97], v[146:149], v[170:173], v[94:97]
	v_mfma_f32_16x16x32_bf16 v[90:93], v[154:157], v[170:173], v[90:93]
	v_mfma_f32_16x16x32_bf16 v[78:81], v[146:149], v[162:165], v[78:81]
	v_mfma_f32_16x16x32_bf16 v[74:77], v[154:157], v[162:165], v[74:77]
	v_mfma_f32_16x16x32_bf16 v[126:129], v[150:153], v[190:193], v[126:129]
	v_mfma_f32_16x16x32_bf16 v[122:125], v[158:161], v[190:193], v[122:125]
	v_mfma_f32_16x16x32_bf16 v[110:113], v[150:153], v[182:185], v[110:113]
	v_mfma_f32_16x16x32_bf16 v[106:109], v[158:161], v[182:185], v[106:109]
	v_mfma_f32_16x16x32_bf16 v[94:97], v[150:153], v[174:177], v[94:97]
	v_mfma_f32_16x16x32_bf16 v[90:93], v[158:161], v[174:177], v[90:93]
	v_mfma_f32_16x16x32_bf16 v[78:81], v[150:153], v[166:169], v[78:81]
	v_mfma_f32_16x16x32_bf16 v[74:77], v[158:161], v[166:169], v[74:77]
	s_setprio 0
	s_setprio 1
	v_mfma_f32_16x16x32_bf16 v[118:121], v[130:133], v[186:189], v[118:121]
	v_mfma_f32_16x16x32_bf16 v[114:117], v[138:141], v[186:189], v[114:117]
	v_mfma_f32_16x16x32_bf16 v[102:105], v[130:133], v[178:181], v[102:105]
	v_mfma_f32_16x16x32_bf16 v[98:101], v[138:141], v[178:181], v[98:101]
	v_mfma_f32_16x16x32_bf16 v[86:89], v[130:133], v[170:173], v[86:89]
	v_mfma_f32_16x16x32_bf16 v[82:85], v[138:141], v[170:173], v[82:85]
	v_mfma_f32_16x16x32_bf16 v[70:73], v[130:133], v[162:165], v[70:73]
	v_mfma_f32_16x16x32_bf16 v[66:69], v[138:141], v[162:165], v[66:69]
	v_mfma_f32_16x16x32_bf16 v[118:121], v[134:137], v[190:193], v[118:121]
	v_mfma_f32_16x16x32_bf16 v[114:117], v[142:145], v[190:193], v[114:117]
	v_mfma_f32_16x16x32_bf16 v[102:105], v[134:137], v[182:185], v[102:105]
	v_mfma_f32_16x16x32_bf16 v[98:101], v[142:145], v[182:185], v[98:101]
	v_mfma_f32_16x16x32_bf16 v[86:89], v[134:137], v[174:177], v[86:89]
	v_mfma_f32_16x16x32_bf16 v[82:85], v[142:145], v[174:177], v[82:85]
	v_mfma_f32_16x16x32_bf16 v[70:73], v[134:137], v[166:169], v[70:73]
	v_mfma_f32_16x16x32_bf16 v[66:69], v[142:145], v[166:169], v[66:69]
	s_setprio 0
	s_barrier
	ds_read_b128 v[186:189], v215 offset:16384
	ds_read_b128 v[190:193], v215 offset:17408
	ds_read_b128 v[178:181], v215 offset:18432
	ds_read_b128 v[182:185], v215 offset:19456
	ds_read_b128 v[170:173], v215 offset:20480
	ds_read_b128 v[174:177], v215 offset:21504
	ds_read_b128 v[162:165], v215 offset:22528
	ds_read_b128 v[166:169], v215 offset:23552
	s_mov_b32 m0, s49
	s_nop 0
	global_load_lds_dwordx4 v211, s[36:37]
	s_add_u32 s40, s36, 0x40000
	s_mov_b32 m0, s50
	s_nop 0
	global_load_lds_dwordx4 v213, s[36:37]
	s_addc_u32 s41, s37, 0
	s_mov_b32 m0, s51
	s_nop 0
	global_load_lds_dwordx4 v211, s[40:41]
	s_and_b64 vcc, exec, s[34:35]
	s_mov_b32 m0, s52
	s_nop 0
	global_load_lds_dwordx4 v213, s[40:41]
	s_mov_b64 s[40:41], -1
	s_mov_b32 m0, s48
	s_nop 0
	global_load_lds_dwordx4 v210, s[38:39]
	s_nop 0
	s_mov_b32 m0, s53
	s_nop 0
	global_load_lds_dwordx4 v212, s[38:39]
	s_cbranch_vccz .LBB0_200
	s_cmp_lg_i32 s93, -2
	s_cbranch_scc1 .Lwin1_n
	s_cmp_lt_u32 s74, 2
	s_cbranch_scc1 .Lwin1_n
	s_waitcnt vmcnt(22)
	s_branch .Lwin1_d

.Lwin1_d:
	s_mov_b64 s[40:41], 0

.LBB0_603:
	v_add_u32_e32 v138, 0x10000, v217
	v_add_u32_e32 v158, 0x14000, v217
	ds_read_b128 v[122:125], v138
	ds_read_b128 v[126:129], v138 offset:1024
	ds_read_b128 v[130:133], v138 offset:2048
	ds_read_b128 v[138:141], v138 offset:3072
	ds_read_b128 v[146:149], v158
	ds_read_b128 v[150:153], v158 offset:1024
	ds_read_b128 v[154:157], v158 offset:2048
	ds_read_b128 v[158:161], v158 offset:3072
	s_cmp_eq_u32 s67, 12
	s_cselect_b32 s28, s7, s63
	s_cselect_b32 s29, s1, s64
	s_cselect_b32 s26, s19, s65
	s_cselect_b32 s27, s17, s66
	s_add_u32 s24, s28, 0x80
	s_addc_u32 s25, s29, 0
	ds_read_b128 v[162:165], v218
	ds_read_b128 v[166:169], v218 offset:1024
	ds_read_b128 v[170:173], v218 offset:2048
	ds_read_b128 v[174:177], v218 offset:3072
	ds_read_b128 v[178:181], v218 offset:4096
	ds_read_b128 v[182:185], v218 offset:5120
	ds_read_b128 v[186:189], v218 offset:6144
	ds_read_b128 v[190:193], v218 offset:7168
	s_mov_b32 m0, s56
	s_nop 0
	global_load_lds_dwordx4 v0, s[2:3]
	s_nop 0
	s_mov_b32 m0, s58
	s_nop 0
	global_load_lds_dwordx4 v215, s[2:3]
	s_cmp_lg_i32 s67, -2
	s_cbranch_scc1 .Lwout0_n
	s_cmp_lt_u32 s57, 2
	s_cbranch_scc1 .Lwout0_n
	s_waitcnt vmcnt(38)
	s_branch .Lwout0_d

.Lwout0_d:
	s_waitcnt lgkmcnt(0)
	s_barrier
	s_setprio 1
	s_waitcnt lgkmcnt(7)
	v_mfma_f32_16x16x32_bf16 v[142:145], v[122:125], v[162:165], v[142:145]
	v_mfma_f32_16x16x32_bf16 v[134:137], v[130:133], v[162:165], v[134:137]
	s_waitcnt lgkmcnt(5)
	v_mfma_f32_16x16x32_bf16 v[110:113], v[122:125], v[170:173], v[110:113]
	v_mfma_f32_16x16x32_bf16 v[106:109], v[130:133], v[170:173], v[106:109]
	s_waitcnt lgkmcnt(3)
	v_mfma_f32_16x16x32_bf16 v[94:97], v[122:125], v[178:181], v[94:97]
	v_mfma_f32_16x16x32_bf16 v[90:93], v[130:133], v[178:181], v[90:93]
	s_waitcnt lgkmcnt(1)
	v_mfma_f32_16x16x32_bf16 v[78:81], v[122:125], v[186:189], v[78:81]
	v_mfma_f32_16x16x32_bf16 v[74:77], v[130:133], v[186:189], v[74:77]
	v_mfma_f32_16x16x32_bf16 v[142:145], v[126:129], v[166:169], v[142:145]
	v_mfma_f32_16x16x32_bf16 v[134:137], v[138:141], v[166:169], v[134:137]
	v_mfma_f32_16x16x32_bf16 v[110:113], v[126:129], v[174:177], v[110:113]
	v_mfma_f32_16x16x32_bf16 v[106:109], v[138:141], v[174:177], v[106:109]
	v_mfma_f32_16x16x32_bf16 v[94:97], v[126:129], v[182:185], v[94:97]
	v_mfma_f32_16x16x32_bf16 v[90:93], v[138:141], v[182:185], v[90:93]
	s_waitcnt lgkmcnt(0)
	v_mfma_f32_16x16x32_bf16 v[78:81], v[126:129], v[190:193], v[78:81]
	v_mfma_f32_16x16x32_bf16 v[74:77], v[138:141], v[190:193], v[74:77]
	s_setprio 0
	s_setprio 1
	v_mfma_f32_16x16x32_bf16 v[118:121], v[146:149], v[162:165], v[118:121]
	v_mfma_f32_16x16x32_bf16 v[114:117], v[154:157], v[162:165], v[114:117]
	v_mfma_f32_16x16x32_bf16 v[102:105], v[146:149], v[170:173], v[102:105]
	v_mfma_f32_16x16x32_bf16 v[98:101], v[154:157], v[170:173], v[98:101]
	v_mfma_f32_16x16x32_bf16 v[86:89], v[146:149], v[178:181], v[86:89]
	v_mfma_f32_16x16x32_bf16 v[82:85], v[154:157], v[178:181], v[82:85]
	v_mfma_f32_16x16x32_bf16 v[70:73], v[146:149], v[186:189], v[70:73]
	v_mfma_f32_16x16x32_bf16 v[66:69], v[154:157], v[186:189], v[66:69]
	v_mfma_f32_16x16x32_bf16 v[118:121], v[150:153], v[166:169], v[118:121]
	v_mfma_f32_16x16x32_bf16 v[114:117], v[158:161], v[166:169], v[114:117]
	v_mfma_f32_16x16x32_bf16 v[102:105], v[150:153], v[174:177], v[102:105]
	v_mfma_f32_16x16x32_bf16 v[98:101], v[158:161], v[174:177], v[98:101]
	v_mfma_f32_16x16x32_bf16 v[86:89], v[150:153], v[182:185], v[86:89]
	v_mfma_f32_16x16x32_bf16 v[82:85], v[158:161], v[182:185], v[82:85]
	v_mfma_f32_16x16x32_bf16 v[70:73], v[150:153], v[190:193], v[70:73]
	v_mfma_f32_16x16x32_bf16 v[66:69], v[158:161], v[190:193], v[66:69]
	s_setprio 0
	s_barrier
	ds_read_b128 v[162:165], v218 offset:16384
	ds_read_b128 v[166:169], v218 offset:17408
	ds_read_b128 v[170:173], v218 offset:18432
	ds_read_b128 v[174:177], v218 offset:19456
	ds_read_b128 v[178:181], v218 offset:20480
	ds_read_b128 v[182:185], v218 offset:21504
	ds_read_b128 v[186:189], v218 offset:22528
	ds_read_b128 v[190:193], v218 offset:23552
	s_mov_b32 m0, s39
	s_nop 0
	global_load_lds_dwordx4 v214, s[26:27]
	s_add_u32 s68, s26, 0x40000
	s_mov_b32 m0, s40
	s_nop 0
	global_load_lds_dwordx4 v216, s[26:27]
	s_addc_u32 s69, s27, 0
	s_mov_b32 m0, s41
	s_nop 0
	global_load_lds_dwordx4 v214, s[68:69]
	s_nop 0
	s_mov_b32 m0, s42
	s_nop 0
	global_load_lds_dwordx4 v216, s[68:69]
	s_nop 0
	s_mov_b32 m0, s38
	s_nop 0
	global_load_lds_dwordx4 v0, s[28:29]
	s_nop 0
	s_mov_b32 m0, s43
	s_nop 0
	global_load_lds_dwordx4 v215, s[28:29]
	s_cmp_lg_i32 s67, -2
	s_cbranch_scc1 .Lwout1_n
	s_cmp_lt_u32 s57, 2
	s_cbranch_scc1 .Lwout1_n
	s_waitcnt vmcnt(38)
	s_branch .Lwout1_d

.Lwout1_d:
	s_waitcnt lgkmcnt(0)
	s_barrier
	s_setprio 1
	s_waitcnt lgkmcnt(7)
	v_mfma_f32_16x16x32_bf16 v[62:65], v[122:125], v[162:165], v[62:65]
	v_mfma_f32_16x16x32_bf16 v[58:61], v[130:133], v[162:165], v[58:61]
	s_waitcnt lgkmcnt(5)
	v_mfma_f32_16x16x32_bf16 v[46:49], v[122:125], v[170:173], v[46:49]
	v_mfma_f32_16x16x32_bf16 v[42:45], v[130:133], v[170:173], v[42:45]
	s_waitcnt lgkmcnt(3)
	v_mfma_f32_16x16x32_bf16 v[30:33], v[122:125], v[178:181], v[30:33]
	v_mfma_f32_16x16x32_bf16 v[26:29], v[130:133], v[178:181], v[26:29]
	s_waitcnt lgkmcnt(1)
	v_mfma_f32_16x16x32_bf16 v[14:17], v[122:125], v[186:189], v[14:17]
	v_mfma_f32_16x16x32_bf16 v[10:13], v[130:133], v[186:189], v[10:13]
	v_mfma_f32_16x16x32_bf16 v[62:65], v[126:129], v[166:169], v[62:65]
	v_mfma_f32_16x16x32_bf16 v[58:61], v[138:141], v[166:169], v[58:61]
	v_mfma_f32_16x16x32_bf16 v[46:49], v[126:129], v[174:177], v[46:49]
	v_mfma_f32_16x16x32_bf16 v[42:45], v[138:141], v[174:177], v[42:45]
	v_mfma_f32_16x16x32_bf16 v[30:33], v[126:129], v[182:185], v[30:33]
	v_mfma_f32_16x16x32_bf16 v[26:29], v[138:141], v[182:185], v[26:29]
	s_waitcnt lgkmcnt(0)
	v_mfma_f32_16x16x32_bf16 v[14:17], v[126:129], v[190:193], v[14:17]
	v_mfma_f32_16x16x32_bf16 v[10:13], v[138:141], v[190:193], v[10:13]
	s_setprio 0
	s_setprio 1
	v_mfma_f32_16x16x32_bf16 v[54:57], v[146:149], v[162:165], v[54:57]
	v_mfma_f32_16x16x32_bf16 v[50:53], v[154:157], v[162:165], v[50:53]
	v_mfma_f32_16x16x32_bf16 v[38:41], v[146:149], v[170:173], v[38:41]
	v_mfma_f32_16x16x32_bf16 v[34:37], v[154:157], v[170:173], v[34:37]
	v_mfma_f32_16x16x32_bf16 v[22:25], v[146:149], v[178:181], v[22:25]
	v_mfma_f32_16x16x32_bf16 v[18:21], v[154:157], v[178:181], v[18:21]
	v_mfma_f32_16x16x32_bf16 v[6:9], v[146:149], v[186:189], v[6:9]
	v_mfma_f32_16x16x32_bf16 v[2:5], v[154:157], v[186:189], v[2:5]
	v_mfma_f32_16x16x32_bf16 v[54:57], v[150:153], v[166:169], v[54:57]
	v_mfma_f32_16x16x32_bf16 v[50:53], v[158:161], v[166:169], v[50:53]
	v_mfma_f32_16x16x32_bf16 v[38:41], v[150:153], v[174:177], v[38:41]
	v_mfma_f32_16x16x32_bf16 v[34:37], v[158:161], v[174:177], v[34:37]
	v_mfma_f32_16x16x32_bf16 v[22:25], v[150:153], v[182:185], v[22:25]
	v_mfma_f32_16x16x32_bf16 v[18:21], v[158:161], v[182:185], v[18:21]
	v_mfma_f32_16x16x32_bf16 v[6:9], v[150:153], v[190:193], v[6:9]
	v_mfma_f32_16x16x32_bf16 v[2:5], v[158:161], v[190:193], v[2:5]
	s_setprio 0
	s_barrier
	v_add_u32_e32 v138, 0x18000, v217
	v_add_u32_e32 v158, 0x1c000, v217
	ds_read_b128 v[122:125], v138
	ds_read_b128 v[126:129], v138 offset:1024
	ds_read_b128 v[130:133], v138 offset:2048
	ds_read_b128 v[138:141], v138 offset:3072
	ds_read_b128 v[146:149], v158
	ds_read_b128 v[150:153], v158 offset:1024
	ds_read_b128 v[154:157], v158 offset:2048
	ds_read_b128 v[158:161], v158 offset:3072
	ds_read_b128 v[162:165], v218 offset:32768
	ds_read_b128 v[166:169], v218 offset:33792
	ds_read_b128 v[170:173], v218 offset:34816
	ds_read_b128 v[174:177], v218 offset:35840
	ds_read_b128 v[178:181], v218 offset:36864
	ds_read_b128 v[182:185], v218 offset:37888
	ds_read_b128 v[186:189], v218 offset:38912
	ds_read_b128 v[190:193], v218 offset:39936
	s_add_u32 s28, s28, 0x40000
	s_addc_u32 s29, s29, 0
	s_mov_b32 m0, s44
	s_nop 0
	global_load_lds_dwordx4 v0, s[28:29]
	s_nop 0
	s_mov_b32 m0, s45
	s_nop 0
	global_load_lds_dwordx4 v215, s[28:29]
	s_waitcnt vmcnt(8)
	s_waitcnt lgkmcnt(0)
	s_barrier
	s_setprio 1
	s_waitcnt lgkmcnt(7)
	v_mfma_f32_16x16x32_bf16 v[142:145], v[122:125], v[162:165], v[142:145]
	v_mfma_f32_16x16x32_bf16 v[134:137], v[130:133], v[162:165], v[134:137]
	s_waitcnt lgkmcnt(5)
	v_mfma_f32_16x16x32_bf16 v[110:113], v[122:125], v[170:173], v[110:113]
	v_mfma_f32_16x16x32_bf16 v[106:109], v[130:133], v[170:173], v[106:109]
	s_waitcnt lgkmcnt(3)
	v_mfma_f32_16x16x32_bf16 v[94:97], v[122:125], v[178:181], v[94:97]
	v_mfma_f32_16x16x32_bf16 v[90:93], v[130:133], v[178:181], v[90:93]
	s_waitcnt lgkmcnt(1)
	v_mfma_f32_16x16x32_bf16 v[78:81], v[122:125], v[186:189], v[78:81]
	v_mfma_f32_16x16x32_bf16 v[74:77], v[130:133], v[186:189], v[74:77]
	v_mfma_f32_16x16x32_bf16 v[142:145], v[126:129], v[166:169], v[142:145]
	v_mfma_f32_16x16x32_bf16 v[134:137], v[138:141], v[166:169], v[134:137]
	v_mfma_f32_16x16x32_bf16 v[110:113], v[126:129], v[174:177], v[110:113]
	v_mfma_f32_16x16x32_bf16 v[106:109], v[138:141], v[174:177], v[106:109]
	v_mfma_f32_16x16x32_bf16 v[94:97], v[126:129], v[182:185], v[94:97]
	v_mfma_f32_16x16x32_bf16 v[90:93], v[138:141], v[182:185], v[90:93]
	s_waitcnt lgkmcnt(0)
	v_mfma_f32_16x16x32_bf16 v[78:81], v[126:129], v[190:193], v[78:81]
	v_mfma_f32_16x16x32_bf16 v[74:77], v[138:141], v[190:193], v[74:77]
	s_setprio 0
	s_setprio 1
	v_mfma_f32_16x16x32_bf16 v[118:121], v[146:149], v[162:165], v[118:121]
	v_mfma_f32_16x16x32_bf16 v[114:117], v[154:157], v[162:165], v[114:117]
	v_mfma_f32_16x16x32_bf16 v[102:105], v[146:149], v[170:173], v[102:105]
	v_mfma_f32_16x16x32_bf16 v[98:101], v[154:157], v[170:173], v[98:101]
	v_mfma_f32_16x16x32_bf16 v[86:89], v[146:149], v[178:181], v[86:89]
	v_mfma_f32_16x16x32_bf16 v[82:85], v[154:157], v[178:181], v[82:85]
	v_mfma_f32_16x16x32_bf16 v[70:73], v[146:149], v[186:189], v[70:73]
	v_mfma_f32_16x16x32_bf16 v[66:69], v[154:157], v[186:189], v[66:69]
	v_mfma_f32_16x16x32_bf16 v[118:121], v[150:153], v[166:169], v[118:121]
	v_mfma_f32_16x16x32_bf16 v[114:117], v[158:161], v[166:169], v[114:117]
	v_mfma_f32_16x16x32_bf16 v[102:105], v[150:153], v[174:177], v[102:105]
	v_mfma_f32_16x16x32_bf16 v[98:101], v[158:161], v[174:177], v[98:101]
	v_mfma_f32_16x16x32_bf16 v[86:89], v[150:153], v[182:185], v[86:89]
	v_mfma_f32_16x16x32_bf16 v[82:85], v[158:161], v[182:185], v[82:85]
	v_mfma_f32_16x16x32_bf16 v[70:73], v[150:153], v[190:193], v[70:73]
	v_mfma_f32_16x16x32_bf16 v[66:69], v[158:161], v[190:193], v[66:69]
	s_setprio 0
	s_barrier
	ds_read_b128 v[162:165], v218 offset:49152
	ds_read_b128 v[166:169], v218 offset:50176
	ds_read_b128 v[170:173], v218 offset:51200
	ds_read_b128 v[174:177], v218 offset:52224
	ds_read_b128 v[178:181], v218 offset:53248
	ds_read_b128 v[182:185], v218 offset:54272
	ds_read_b128 v[186:189], v218 offset:55296
	ds_read_b128 v[190:193], v218 offset:56320
	s_add_u32 s28, s26, 0x80
	s_addc_u32 s29, s27, 0
	s_mov_b32 m0, s50
	s_nop 0
	global_load_lds_dwordx4 v214, s[28:29]
	s_add_u32 s26, s26, 0x40080
	s_mov_b32 m0, s51
	s_nop 0
	global_load_lds_dwordx4 v216, s[28:29]
	s_addc_u32 s27, s27, 0
	s_mov_b32 m0, s54
	s_nop 0
	global_load_lds_dwordx4 v214, s[26:27]
	s_nop 0
	s_mov_b32 m0, s55
	s_nop 0
	global_load_lds_dwordx4 v216, s[26:27]
	s_nop 0
	s_mov_b32 m0, s52
	s_nop 0
	global_load_lds_dwordx4 v0, s[24:25]
	s_nop 0
	s_mov_b32 m0, s53
	s_nop 0
	global_load_lds_dwordx4 v215, s[24:25]
	s_waitcnt vmcnt(8)
	s_waitcnt lgkmcnt(0)
	s_barrier
	s_setprio 1
	s_waitcnt lgkmcnt(7)
	v_mfma_f32_16x16x32_bf16 v[62:65], v[122:125], v[162:165], v[62:65]
	v_mfma_f32_16x16x32_bf16 v[58:61], v[130:133], v[162:165], v[58:61]
	s_waitcnt lgkmcnt(5)
	v_mfma_f32_16x16x32_bf16 v[46:49], v[122:125], v[170:173], v[46:49]
	v_mfma_f32_16x16x32_bf16 v[42:45], v[130:133], v[170:173], v[42:45]
	s_waitcnt lgkmcnt(3)
	v_mfma_f32_16x16x32_bf16 v[30:33], v[122:125], v[178:181], v[30:33]
	v_mfma_f32_16x16x32_bf16 v[26:29], v[130:133], v[178:181], v[26:29]
	s_waitcnt lgkmcnt(1)
	v_mfma_f32_16x16x32_bf16 v[14:17], v[122:125], v[186:189], v[14:17]
	v_mfma_f32_16x16x32_bf16 v[10:13], v[130:133], v[186:189], v[10:13]
	v_mfma_f32_16x16x32_bf16 v[62:65], v[126:129], v[166:169], v[62:65]
	v_mfma_f32_16x16x32_bf16 v[58:61], v[138:141], v[166:169], v[58:61]
	v_mfma_f32_16x16x32_bf16 v[46:49], v[126:129], v[174:177], v[46:49]
	v_mfma_f32_16x16x32_bf16 v[42:45], v[138:141], v[174:177], v[42:45]
	v_mfma_f32_16x16x32_bf16 v[30:33], v[126:129], v[182:185], v[30:33]
	v_mfma_f32_16x16x32_bf16 v[26:29], v[138:141], v[182:185], v[26:29]
	s_waitcnt lgkmcnt(0)
	v_mfma_f32_16x16x32_bf16 v[14:17], v[126:129], v[190:193], v[14:17]
	v_mfma_f32_16x16x32_bf16 v[10:13], v[138:141], v[190:193], v[10:13]
	s_setprio 0
	s_setprio 1
	v_mfma_f32_16x16x32_bf16 v[54:57], v[146:149], v[162:165], v[54:57]
	v_mfma_f32_16x16x32_bf16 v[50:53], v[154:157], v[162:165], v[50:53]
	v_mfma_f32_16x16x32_bf16 v[38:41], v[146:149], v[170:173], v[38:41]
	v_mfma_f32_16x16x32_bf16 v[34:37], v[154:157], v[170:173], v[34:37]
	v_mfma_f32_16x16x32_bf16 v[22:25], v[146:149], v[178:181], v[22:25]
	v_mfma_f32_16x16x32_bf16 v[18:21], v[154:157], v[178:181], v[18:21]
	v_mfma_f32_16x16x32_bf16 v[6:9], v[146:149], v[186:189], v[6:9]
	v_mfma_f32_16x16x32_bf16 v[2:5], v[154:157], v[186:189], v[2:5]
	v_mfma_f32_16x16x32_bf16 v[54:57], v[150:153], v[166:169], v[54:57]
	v_mfma_f32_16x16x32_bf16 v[50:53], v[158:161], v[166:169], v[50:53]
	v_mfma_f32_16x16x32_bf16 v[38:41], v[150:153], v[174:177], v[38:41]
	v_mfma_f32_16x16x32_bf16 v[34:37], v[158:161], v[174:177], v[34:37]
	v_mfma_f32_16x16x32_bf16 v[22:25], v[150:153], v[182:185], v[22:25]
	v_mfma_f32_16x16x32_bf16 v[18:21], v[158:161], v[182:185], v[18:21]
	v_mfma_f32_16x16x32_bf16 v[6:9], v[150:153], v[190:193], v[6:9]
	v_mfma_f32_16x16x32_bf16 v[2:5], v[158:161], v[190:193], v[2:5]
	s_setprio 0
	s_barrier
	s_add_i32 s67, s67, 2
	s_add_u32 s63, s63, 0x100
	s_addc_u32 s64, s64, 0
	s_add_u32 s65, s65, 0x100
	s_addc_u32 s66, s66, 0
	s_add_u32 s2, s2, 0x100
	s_addc_u32 s3, s3, 0
	s_cmp_gt_u32 s67, 13
	s_cbranch_scc0 .LBB0_603
	s_and_b64 vcc, exec, s[12:13]
	s_cbranch_vccz .LBB0_606
	s_barrier

.LBB0_898:
	v_add_u32_e32 v138, 0x10000, v217
	v_add_u32_e32 v158, 0x14000, v217
	ds_read_b128 v[122:125], v138
	ds_read_b128 v[126:129], v138 offset:1024
	ds_read_b128 v[130:133], v138 offset:2048
	ds_read_b128 v[138:141], v138 offset:3072
	ds_read_b128 v[146:149], v158
	ds_read_b128 v[150:153], v158 offset:1024
	ds_read_b128 v[154:157], v158 offset:2048
	ds_read_b128 v[158:161], v158 offset:3072
	s_cmp_eq_u32 s63, 40
	s_cselect_b32 s22, s6, s59
	s_cselect_b32 s23, s7, s60
	s_cselect_b32 s20, s16, s61
	s_cselect_b32 s21, s17, s62
	s_add_u32 s18, s22, 0x80
	s_addc_u32 s19, s23, 0
	ds_read_b128 v[162:165], v218
	ds_read_b128 v[166:169], v218 offset:1024
	ds_read_b128 v[170:173], v218 offset:2048
	ds_read_b128 v[174:177], v218 offset:3072
	ds_read_b128 v[178:181], v218 offset:4096
	ds_read_b128 v[182:185], v218 offset:5120
	ds_read_b128 v[186:189], v218 offset:6144
	ds_read_b128 v[190:193], v218 offset:7168
	s_mov_b32 m0, s50
	s_nop 0
	global_load_lds_dwordx4 v0, s[2:3]
	s_nop 0
	s_mov_b32 m0, s52
	s_nop 0
	global_load_lds_dwordx4 v215, s[2:3]
	s_cmp_lg_i32 s63, -2
	s_cbranch_scc1 .Lwdn0_n
	s_cmp_lt_u32 s51, 2
	s_cbranch_scc1 .Lwdn0_n
	s_waitcnt vmcnt(38)
	s_branch .Lwdn0_d

.Lwdn0_d:
	s_waitcnt lgkmcnt(0)
	s_barrier
	s_setprio 1
	s_waitcnt lgkmcnt(7)
	v_mfma_f32_16x16x32_bf16 v[142:145], v[122:125], v[162:165], v[142:145]
	v_mfma_f32_16x16x32_bf16 v[134:137], v[130:133], v[162:165], v[134:137]
	s_waitcnt lgkmcnt(5)
	v_mfma_f32_16x16x32_bf16 v[110:113], v[122:125], v[170:173], v[110:113]
	v_mfma_f32_16x16x32_bf16 v[106:109], v[130:133], v[170:173], v[106:109]
	s_waitcnt lgkmcnt(3)
	v_mfma_f32_16x16x32_bf16 v[94:97], v[122:125], v[178:181], v[94:97]
	v_mfma_f32_16x16x32_bf16 v[90:93], v[130:133], v[178:181], v[90:93]
	s_waitcnt lgkmcnt(1)
	v_mfma_f32_16x16x32_bf16 v[78:81], v[122:125], v[186:189], v[78:81]
	v_mfma_f32_16x16x32_bf16 v[74:77], v[130:133], v[186:189], v[74:77]
	v_mfma_f32_16x16x32_bf16 v[142:145], v[126:129], v[166:169], v[142:145]
	v_mfma_f32_16x16x32_bf16 v[134:137], v[138:141], v[166:169], v[134:137]
	v_mfma_f32_16x16x32_bf16 v[110:113], v[126:129], v[174:177], v[110:113]
	v_mfma_f32_16x16x32_bf16 v[106:109], v[138:141], v[174:177], v[106:109]
	v_mfma_f32_16x16x32_bf16 v[94:97], v[126:129], v[182:185], v[94:97]
	v_mfma_f32_16x16x32_bf16 v[90:93], v[138:141], v[182:185], v[90:93]
	s_waitcnt lgkmcnt(0)
	v_mfma_f32_16x16x32_bf16 v[78:81], v[126:129], v[190:193], v[78:81]
	v_mfma_f32_16x16x32_bf16 v[74:77], v[138:141], v[190:193], v[74:77]
	s_setprio 0
	s_setprio 1
	v_mfma_f32_16x16x32_bf16 v[118:121], v[146:149], v[162:165], v[118:121]
	v_mfma_f32_16x16x32_bf16 v[114:117], v[154:157], v[162:165], v[114:117]
	v_mfma_f32_16x16x32_bf16 v[102:105], v[146:149], v[170:173], v[102:105]
	v_mfma_f32_16x16x32_bf16 v[98:101], v[154:157], v[170:173], v[98:101]
	v_mfma_f32_16x16x32_bf16 v[86:89], v[146:149], v[178:181], v[86:89]
	v_mfma_f32_16x16x32_bf16 v[82:85], v[154:157], v[178:181], v[82:85]
	v_mfma_f32_16x16x32_bf16 v[70:73], v[146:149], v[186:189], v[70:73]
	v_mfma_f32_16x16x32_bf16 v[66:69], v[154:157], v[186:189], v[66:69]
	v_mfma_f32_16x16x32_bf16 v[118:121], v[150:153], v[166:169], v[118:121]
	v_mfma_f32_16x16x32_bf16 v[114:117], v[158:161], v[166:169], v[114:117]
	v_mfma_f32_16x16x32_bf16 v[102:105], v[150:153], v[174:177], v[102:105]
	v_mfma_f32_16x16x32_bf16 v[98:101], v[158:161], v[174:177], v[98:101]
	v_mfma_f32_16x16x32_bf16 v[86:89], v[150:153], v[182:185], v[86:89]
	v_mfma_f32_16x16x32_bf16 v[82:85], v[158:161], v[182:185], v[82:85]
	v_mfma_f32_16x16x32_bf16 v[70:73], v[150:153], v[190:193], v[70:73]
	v_mfma_f32_16x16x32_bf16 v[66:69], v[158:161], v[190:193], v[66:69]
	s_setprio 0
	s_barrier
	ds_read_b128 v[162:165], v218 offset:16384
	ds_read_b128 v[166:169], v218 offset:17408
	ds_read_b128 v[170:173], v218 offset:18432
	ds_read_b128 v[174:177], v218 offset:19456
	ds_read_b128 v[178:181], v218 offset:20480
	ds_read_b128 v[182:185], v218 offset:21504
	ds_read_b128 v[186:189], v218 offset:22528
	ds_read_b128 v[190:193], v218 offset:23552
	s_mov_b32 m0, s31
	s_nop 0
	global_load_lds_dwordx4 v214, s[20:21]
	s_add_u32 s64, s20, 0xb4000
	s_mov_b32 m0, s34
	s_nop 0
	global_load_lds_dwordx4 v216, s[20:21]
	s_addc_u32 s65, s21, 0
	s_mov_b32 m0, s35
	s_nop 0
	global_load_lds_dwordx4 v214, s[64:65]
	s_nop 0
	s_mov_b32 m0, s36
	s_nop 0
	global_load_lds_dwordx4 v216, s[64:65]
	s_nop 0
	s_mov_b32 m0, s30
	s_nop 0
	global_load_lds_dwordx4 v0, s[22:23]
	s_nop 0
	s_mov_b32 m0, s37
	s_nop 0
	global_load_lds_dwordx4 v215, s[22:23]
	s_cmp_lg_i32 s63, -2
	s_cbranch_scc1 .Lwdn1_n
	s_cmp_lt_u32 s51, 2
	s_cbranch_scc1 .Lwdn1_n
	s_waitcnt vmcnt(38)
	s_branch .Lwdn1_d

.Lwdn1_d:
	s_waitcnt lgkmcnt(0)
	s_barrier
	s_setprio 1
	s_waitcnt lgkmcnt(7)
	v_mfma_f32_16x16x32_bf16 v[62:65], v[122:125], v[162:165], v[62:65]
	v_mfma_f32_16x16x32_bf16 v[58:61], v[130:133], v[162:165], v[58:61]
	s_waitcnt lgkmcnt(5)
	v_mfma_f32_16x16x32_bf16 v[46:49], v[122:125], v[170:173], v[46:49]
	v_mfma_f32_16x16x32_bf16 v[42:45], v[130:133], v[170:173], v[42:45]
	s_waitcnt lgkmcnt(3)
	v_mfma_f32_16x16x32_bf16 v[30:33], v[122:125], v[178:181], v[30:33]
	v_mfma_f32_16x16x32_bf16 v[26:29], v[130:133], v[178:181], v[26:29]
	s_waitcnt lgkmcnt(1)
	v_mfma_f32_16x16x32_bf16 v[14:17], v[122:125], v[186:189], v[14:17]
	v_mfma_f32_16x16x32_bf16 v[10:13], v[130:133], v[186:189], v[10:13]
	v_mfma_f32_16x16x32_bf16 v[62:65], v[126:129], v[166:169], v[62:65]
	v_mfma_f32_16x16x32_bf16 v[58:61], v[138:141], v[166:169], v[58:61]
	v_mfma_f32_16x16x32_bf16 v[46:49], v[126:129], v[174:177], v[46:49]
	v_mfma_f32_16x16x32_bf16 v[42:45], v[138:141], v[174:177], v[42:45]
	v_mfma_f32_16x16x32_bf16 v[30:33], v[126:129], v[182:185], v[30:33]
	v_mfma_f32_16x16x32_bf16 v[26:29], v[138:141], v[182:185], v[26:29]
	s_waitcnt lgkmcnt(0)
	v_mfma_f32_16x16x32_bf16 v[14:17], v[126:129], v[190:193], v[14:17]
	v_mfma_f32_16x16x32_bf16 v[10:13], v[138:141], v[190:193], v[10:13]
	s_setprio 0
	s_setprio 1
	v_mfma_f32_16x16x32_bf16 v[54:57], v[146:149], v[162:165], v[54:57]
	v_mfma_f32_16x16x32_bf16 v[50:53], v[154:157], v[162:165], v[50:53]
	v_mfma_f32_16x16x32_bf16 v[38:41], v[146:149], v[170:173], v[38:41]
	v_mfma_f32_16x16x32_bf16 v[34:37], v[154:157], v[170:173], v[34:37]
	v_mfma_f32_16x16x32_bf16 v[22:25], v[146:149], v[178:181], v[22:25]
	v_mfma_f32_16x16x32_bf16 v[18:21], v[154:157], v[178:181], v[18:21]
	v_mfma_f32_16x16x32_bf16 v[6:9], v[146:149], v[186:189], v[6:9]
	v_mfma_f32_16x16x32_bf16 v[2:5], v[154:157], v[186:189], v[2:5]
	v_mfma_f32_16x16x32_bf16 v[54:57], v[150:153], v[166:169], v[54:57]
	v_mfma_f32_16x16x32_bf16 v[50:53], v[158:161], v[166:169], v[50:53]
	v_mfma_f32_16x16x32_bf16 v[38:41], v[150:153], v[174:177], v[38:41]
	v_mfma_f32_16x16x32_bf16 v[34:37], v[158:161], v[174:177], v[34:37]
	v_mfma_f32_16x16x32_bf16 v[22:25], v[150:153], v[182:185], v[22:25]
	v_mfma_f32_16x16x32_bf16 v[18:21], v[158:161], v[182:185], v[18:21]
	v_mfma_f32_16x16x32_bf16 v[6:9], v[150:153], v[190:193], v[6:9]
	v_mfma_f32_16x16x32_bf16 v[2:5], v[158:161], v[190:193], v[2:5]
	s_setprio 0
	s_barrier
	v_add_u32_e32 v138, 0x18000, v217
	v_add_u32_e32 v158, 0x1c000, v217
	ds_read_b128 v[122:125], v138
	ds_read_b128 v[126:129], v138 offset:1024
	ds_read_b128 v[130:133], v138 offset:2048
	ds_read_b128 v[138:141], v138 offset:3072
	ds_read_b128 v[146:149], v158
	ds_read_b128 v[150:153], v158 offset:1024
	ds_read_b128 v[154:157], v158 offset:2048
	ds_read_b128 v[158:161], v158 offset:3072
	ds_read_b128 v[162:165], v218 offset:32768
	ds_read_b128 v[166:169], v218 offset:33792
	ds_read_b128 v[170:173], v218 offset:34816
	ds_read_b128 v[174:177], v218 offset:35840
	ds_read_b128 v[178:181], v218 offset:36864
	ds_read_b128 v[182:185], v218 offset:37888
	ds_read_b128 v[186:189], v218 offset:38912
	ds_read_b128 v[190:193], v218 offset:39936
	s_add_u32 s22, s22, 0xb4000
	s_addc_u32 s23, s23, 0
	s_mov_b32 m0, s38
	s_nop 0
	global_load_lds_dwordx4 v0, s[22:23]
	s_nop 0
	s_mov_b32 m0, s39
	s_nop 0
	global_load_lds_dwordx4 v215, s[22:23]
	s_waitcnt vmcnt(8)
	s_waitcnt lgkmcnt(0)
	s_barrier
	s_setprio 1
	s_waitcnt lgkmcnt(7)
	v_mfma_f32_16x16x32_bf16 v[142:145], v[122:125], v[162:165], v[142:145]
	v_mfma_f32_16x16x32_bf16 v[134:137], v[130:133], v[162:165], v[134:137]
	s_waitcnt lgkmcnt(5)
	v_mfma_f32_16x16x32_bf16 v[110:113], v[122:125], v[170:173], v[110:113]
	v_mfma_f32_16x16x32_bf16 v[106:109], v[130:133], v[170:173], v[106:109]
	s_waitcnt lgkmcnt(3)
	v_mfma_f32_16x16x32_bf16 v[94:97], v[122:125], v[178:181], v[94:97]
	v_mfma_f32_16x16x32_bf16 v[90:93], v[130:133], v[178:181], v[90:93]
	s_waitcnt lgkmcnt(1)
	v_mfma_f32_16x16x32_bf16 v[78:81], v[122:125], v[186:189], v[78:81]
	v_mfma_f32_16x16x32_bf16 v[74:77], v[130:133], v[186:189], v[74:77]
	v_mfma_f32_16x16x32_bf16 v[142:145], v[126:129], v[166:169], v[142:145]
	v_mfma_f32_16x16x32_bf16 v[134:137], v[138:141], v[166:169], v[134:137]
	v_mfma_f32_16x16x32_bf16 v[110:113], v[126:129], v[174:177], v[110:113]
	v_mfma_f32_16x16x32_bf16 v[106:109], v[138:141], v[174:177], v[106:109]
	v_mfma_f32_16x16x32_bf16 v[94:97], v[126:129], v[182:185], v[94:97]
	v_mfma_f32_16x16x32_bf16 v[90:93], v[138:141], v[182:185], v[90:93]
	s_waitcnt lgkmcnt(0)
	v_mfma_f32_16x16x32_bf16 v[78:81], v[126:129], v[190:193], v[78:81]
	v_mfma_f32_16x16x32_bf16 v[74:77], v[138:141], v[190:193], v[74:77]
	s_setprio 0
	s_setprio 1
	v_mfma_f32_16x16x32_bf16 v[118:121], v[146:149], v[162:165], v[118:121]
	v_mfma_f32_16x16x32_bf16 v[114:117], v[154:157], v[162:165], v[114:117]
	v_mfma_f32_16x16x32_bf16 v[102:105], v[146:149], v[170:173], v[102:105]
	v_mfma_f32_16x16x32_bf16 v[98:101], v[154:157], v[170:173], v[98:101]
	v_mfma_f32_16x16x32_bf16 v[86:89], v[146:149], v[178:181], v[86:89]
	v_mfma_f32_16x16x32_bf16 v[82:85], v[154:157], v[178:181], v[82:85]
	v_mfma_f32_16x16x32_bf16 v[70:73], v[146:149], v[186:189], v[70:73]
	v_mfma_f32_16x16x32_bf16 v[66:69], v[154:157], v[186:189], v[66:69]
	v_mfma_f32_16x16x32_bf16 v[118:121], v[150:153], v[166:169], v[118:121]
	v_mfma_f32_16x16x32_bf16 v[114:117], v[158:161], v[166:169], v[114:117]
	v_mfma_f32_16x16x32_bf16 v[102:105], v[150:153], v[174:177], v[102:105]
	v_mfma_f32_16x16x32_bf16 v[98:101], v[158:161], v[174:177], v[98:101]
	v_mfma_f32_16x16x32_bf16 v[86:89], v[150:153], v[182:185], v[86:89]
	v_mfma_f32_16x16x32_bf16 v[82:85], v[158:161], v[182:185], v[82:85]
	v_mfma_f32_16x16x32_bf16 v[70:73], v[150:153], v[190:193], v[70:73]
	v_mfma_f32_16x16x32_bf16 v[66:69], v[158:161], v[190:193], v[66:69]
	s_setprio 0
	s_barrier
	ds_read_b128 v[162:165], v218 offset:49152
	ds_read_b128 v[166:169], v218 offset:50176
	ds_read_b128 v[170:173], v218 offset:51200
	ds_read_b128 v[174:177], v218 offset:52224
	ds_read_b128 v[178:181], v218 offset:53248
	ds_read_b128 v[182:185], v218 offset:54272
	ds_read_b128 v[186:189], v218 offset:55296
	ds_read_b128 v[190:193], v218 offset:56320
	s_add_u32 s22, s20, 0x80
	s_addc_u32 s23, s21, 0
	s_mov_b32 m0, s44
	s_nop 0
	global_load_lds_dwordx4 v214, s[22:23]
	s_add_u32 s20, s20, 0xb4080
	s_mov_b32 m0, s45
	s_nop 0
	global_load_lds_dwordx4 v216, s[22:23]
	s_addc_u32 s21, s21, 0
	s_mov_b32 m0, s48
	s_nop 0
	global_load_lds_dwordx4 v214, s[20:21]
	s_nop 0
	s_mov_b32 m0, s49
	s_nop 0
	global_load_lds_dwordx4 v216, s[20:21]
	s_nop 0
	s_mov_b32 m0, s46
	s_nop 0
	global_load_lds_dwordx4 v0, s[18:19]
	s_nop 0
	s_mov_b32 m0, s47
	s_nop 0
	global_load_lds_dwordx4 v215, s[18:19]
	s_waitcnt vmcnt(8)
	s_waitcnt lgkmcnt(0)
	s_barrier
	s_setprio 1
	s_waitcnt lgkmcnt(7)
	v_mfma_f32_16x16x32_bf16 v[62:65], v[122:125], v[162:165], v[62:65]
	v_mfma_f32_16x16x32_bf16 v[58:61], v[130:133], v[162:165], v[58:61]
	s_waitcnt lgkmcnt(5)
	v_mfma_f32_16x16x32_bf16 v[46:49], v[122:125], v[170:173], v[46:49]
	v_mfma_f32_16x16x32_bf16 v[42:45], v[130:133], v[170:173], v[42:45]
	s_waitcnt lgkmcnt(3)
	v_mfma_f32_16x16x32_bf16 v[30:33], v[122:125], v[178:181], v[30:33]
	v_mfma_f32_16x16x32_bf16 v[26:29], v[130:133], v[178:181], v[26:29]
	s_waitcnt lgkmcnt(1)
	v_mfma_f32_16x16x32_bf16 v[14:17], v[122:125], v[186:189], v[14:17]
	v_mfma_f32_16x16x32_bf16 v[10:13], v[130:133], v[186:189], v[10:13]
	v_mfma_f32_16x16x32_bf16 v[62:65], v[126:129], v[166:169], v[62:65]
	v_mfma_f32_16x16x32_bf16 v[58:61], v[138:141], v[166:169], v[58:61]
	v_mfma_f32_16x16x32_bf16 v[46:49], v[126:129], v[174:177], v[46:49]
	v_mfma_f32_16x16x32_bf16 v[42:45], v[138:141], v[174:177], v[42:45]
	v_mfma_f32_16x16x32_bf16 v[30:33], v[126:129], v[182:185], v[30:33]
	v_mfma_f32_16x16x32_bf16 v[26:29], v[138:141], v[182:185], v[26:29]
	s_waitcnt lgkmcnt(0)
	v_mfma_f32_16x16x32_bf16 v[14:17], v[126:129], v[190:193], v[14:17]
	v_mfma_f32_16x16x32_bf16 v[10:13], v[138:141], v[190:193], v[10:13]
	s_setprio 0
	s_setprio 1
	v_mfma_f32_16x16x32_bf16 v[54:57], v[146:149], v[162:165], v[54:57]
	v_mfma_f32_16x16x32_bf16 v[50:53], v[154:157], v[162:165], v[50:53]
	v_mfma_f32_16x16x32_bf16 v[38:41], v[146:149], v[170:173], v[38:41]
	v_mfma_f32_16x16x32_bf16 v[34:37], v[154:157], v[170:173], v[34:37]
	v_mfma_f32_16x16x32_bf16 v[22:25], v[146:149], v[178:181], v[22:25]
	v_mfma_f32_16x16x32_bf16 v[18:21], v[154:157], v[178:181], v[18:21]
	v_mfma_f32_16x16x32_bf16 v[6:9], v[146:149], v[186:189], v[6:9]
	v_mfma_f32_16x16x32_bf16 v[2:5], v[154:157], v[186:189], v[2:5]
	v_mfma_f32_16x16x32_bf16 v[54:57], v[150:153], v[166:169], v[54:57]
	v_mfma_f32_16x16x32_bf16 v[50:53], v[158:161], v[166:169], v[50:53]
	v_mfma_f32_16x16x32_bf16 v[38:41], v[150:153], v[174:177], v[38:41]
	v_mfma_f32_16x16x32_bf16 v[34:37], v[158:161], v[174:177], v[34:37]
	v_mfma_f32_16x16x32_bf16 v[22:25], v[150:153], v[182:185], v[22:25]
	v_mfma_f32_16x16x32_bf16 v[18:21], v[158:161], v[182:185], v[18:21]
	v_mfma_f32_16x16x32_bf16 v[6:9], v[150:153], v[190:193], v[6:9]
	v_mfma_f32_16x16x32_bf16 v[2:5], v[158:161], v[190:193], v[2:5]
	s_setprio 0
	s_barrier
	s_add_i32 s63, s63, 2
	s_add_u32 s59, s59, 0x100
	s_addc_u32 s60, s60, 0
	s_add_u32 s61, s61, 0x100
	s_addc_u32 s62, s62, 0
	s_add_u32 s2, s2, 0x100
	s_addc_u32 s3, s3, 0
	s_cmp_gt_u32 s63, 41
	s_cbranch_scc0 .LBB0_898
	s_and_b64 vcc, exec, s[12:13]
	s_cbranch_vccz .LBB0_901
	s_barrier
